# speedup vs baseline: 1.0171x; 1.0022x over previous
; __device__ __forceinline__ void wkv_scan(unsigned char* ws, int scan, float* lds, int wv_) {
;     ...
;   const int ks = lane & 7, rp = wave * 8 + (lane >> 3);
;   float* yp = Y + ((size_t)(b * SEQ_ + (dir ? SEQ_ - 1 : 0))) * BW_ + h * 64 + 2 * rp;
;   const long ystep = dir ? -(long)BW_ : (long)BW_;
;   float2v S0[4], S1[4];
; #pragma unroll
;   for (int i = 0; i < 4; ++i) { S0[i] = float2v{0.f, 0.f}; S1[i] = float2v{0.f, 0.f}; }
;   __syncthreads();
;   if (wave >= 4) { pload(0); pstore(0); pload(1); }
;   __syncthreads();
.LBB0_266:
	s_or_b64 exec, exec, s[2:3]
	v_lshrrev_b32_e32 v9, 3, v6
	v_lshl_or_b32 v96, v5, 3, v9
	v_readlane_b32 s2, v252, 56
	v_mov_b32_e32 v97, 0
	v_readlane_b32 s3, v252, 57
	v_lshlrev_b32_e32 v10, 2, v4
	v_and_b32_e32 v9, 7, v6
	v_lshl_add_u64 v[98:99], v[96:97], 2, s[2:3]
	v_readlane_b32 s2, v252, 52
	v_lshlrev_b32_e32 v8, 2, v8
	v_readlane_b32 s3, v252, 53
	v_or_b32_e32 v100, s2, v4
	v_mov_b32_e32 v166, v167
	s_mov_b32 s8, 0
	v_cmp_eq_u32_e64 s[4:5], 0, v9
	v_add3_u32 v82, 0, v8, v10
	v_add_u32_e32 v83, 32, v7
	v_or_b32_e32 v101, s3, v167
	v_lshlrev_b32_e32 v112, 5, v9
	s_movk_i32 s2, 0x500
	v_lshl_add_u32 v113, v96, 2, s2
	v_readlane_b32 s14, v252, 61
	v_readlane_b32 s15, v252, 62
	v_readlane_b32 s100, v252, 59
	v_readlane_b32 s101, v252, 60
	s_nop 1
	v_lshl_add_u64 v[110:111], v[98:99], 0, s[14:15]
	v_mov_b64_e32 v[102:103], v[166:167]
	v_mov_b64_e32 v[104:105], v[166:167]
	v_mov_b64_e32 v[106:107], v[166:167]
	v_mov_b64_e32 v[108:109], v[166:167]
	s_waitcnt lgkmcnt(0)
	s_barrier
	s_branch .LBB0_268

; __device__ __forceinline__ void wkv_scan(unsigned char* ws, int scan, float* lds, int wv_) {
;     ...
;       const float* buf = lds + (c & 1) * (CH * STEPF);
;       const float* sp0 = buf + ks * 8;
;       float4 ra = *(const float4*)(sp0), rb = *(const float4*)(sp0 + 4);
;       float4 wa = *(const float4*)(sp0 + 64), wb = *(const float4*)(sp0 + 68);
;       float4 ka = *(const float4*)(sp0 + 128), kb = *(const float4*)(sp0 + 132);
;       float4 aa = *(const float4*)(sp0 + 192), ab = *(const float4*)(sp0 + 196);
;       float4 ba = *(const float4*)(sp0 + 256), bb = *(const float4*)(sp0 + 260);
;       float2 vv = *(const float2*)(buf + 320 + 2 * rp);
; #pragma unroll 2
;       for (int s = 0; s < CH; ++s) {
;         float2v r2[4] = {{ra.x, ra.y}, {ra.z, ra.w}, {rb.x, rb.y}, {rb.z, rb.w}};
;         float2v w2[4] = {{wa.x, wa.y}, {wa.z, wa.w}, {wb.x, wb.y}, {wb.z, wb.w}};
;         float2v k2[4] = {{ka.x, ka.y}, {ka.z, ka.w}, {kb.x, kb.y}, {kb.z, kb.w}};
;         float2v a2[4] = {{aa.x, aa.y}, {aa.z, aa.w}, {ab.x, ab.y}, {ab.z, ab.w}};
;         float2v b2[4] = {{ba.x, ba.y}, {ba.z, ba.w}, {bb.x, bb.y}, {bb.z, bb.w}};
;         float2v v0v = {vv.x, vv.x}, v1v = {vv.y, vv.y};
;         {
;           const int sn = (s + 1 < CH) ? (s + 1) : s;
;           const float* sp = buf + sn * STEPF + ks * 8;
;           ra = *(const float4*)(sp); rb = *(const float4*)(sp + 4);
;           wa = *(const float4*)(sp + 64); wb = *(const float4*)(sp + 68);
;           ka = *(const float4*)(sp + 128); kb = *(const float4*)(sp + 132);
;           aa = *(const float4*)(sp + 192); ab = *(const float4*)(sp + 196);
;           ba = *(const float4*)(sp + 256); bb = *(const float4*)(sp + 260);
;           vv = *(const float2*)(buf + sn * STEPF + 320 + 2 * rp);
;         }
;         float2v t0 = S0[0] * a2[0], t1 = S1[0] * a2[0];
; #pragma unroll
;         for (int i = 1; i < 4; ++i) { t0 += S0[i] * a2[i]; t1 += S1[i] * a2[i]; }
;         float sa0 = red8(t0.x + t0.y), sa1 = red8(t1.x + t1.y);
;         float2v sa0v = {sa0, sa0}, sa1v = {sa1, sa1};
; #pragma unroll
;         for (int i = 0; i < 4; ++i) {
;           S0[i] = S0[i] * w2[i] + (sa0v * b2[i] + v0v * k2[i]);
;           S1[i] = S1[i] * w2[i] + (sa1v * b2[i] + v1v * k2[i]);
;         }
;         float2v y0 = S0[0] * r2[0], y1 = S1[0] * r2[0];
; #pragma unroll
.LBB0_268:
	s_bitcmp1_b32 s8, 0
	s_cselect_b32 s6, 0x6000, 0
	v_add_u32_e32 v114, s6, v112
	v_add_u32_e32 v115, s6, v113
	ds_read_b128 v[32:35], v114 offset:768
	ds_read_b128 v[36:39], v114 offset:784
	ds_read_b128 v[24:27], v114 offset:512
	ds_read_b128 v[28:31], v114 offset:528
	ds_read_b32 v48, v115
	ds_read_b128 v[40:43], v114 offset:1024
	ds_read_b128 v[44:47], v114 offset:1040
	ds_read_b128 v[16:19], v114 offset:256
	ds_read_b128 v[20:23], v114 offset:272
	ds_read_b128 v[8:11], v114
	ds_read_b128 v[12:15], v114 offset:16
	s_mov_b32 s10, 0
	s_waitcnt lgkmcnt(6)
	v_pk_mul_f32 v[24:25], v[24:25], v[48:49] op_sel_hi:[1,0]
	v_pk_mul_f32 v[26:27], v[26:27], v[48:49] op_sel_hi:[1,0]
	v_pk_mul_f32 v[28:29], v[28:29], v[48:49] op_sel_hi:[1,0]
	v_pk_mul_f32 v[30:31], v[30:31], v[48:49] op_sel_hi:[1,0]
.Lscan8_step:
	v_pk_mul_f32 v[126:127], v[102:103], v[32:33]
	ds_read_b128 v[74:77], v114 offset:2304
	v_pk_fma_f32 v[126:127], v[104:105], v[34:35], v[126:127]
	ds_read_b128 v[78:81], v114 offset:2320
	v_pk_fma_f32 v[126:127], v[106:107], v[36:37], v[126:127]
	ds_read_b128 v[66:69], v114 offset:2048
	v_pk_fma_f32 v[126:127], v[108:109], v[38:39], v[126:127]
	ds_read_b128 v[70:73], v114 offset:2064
	v_add_f32_e32 v126, v126, v127
	ds_read_b32 v124, v115 offset:1536
	ds_read_b128 v[116:119], v114 offset:2560
	v_add_f32_dpp v126, v126, v126 quad_perm:[1,0,3,2] row_mask:0xf bank_mask:0xf bound_ctrl:1
	s_nop 1
	v_add_f32_dpp v126, v126, v126 quad_perm:[2,3,0,1] row_mask:0xf bank_mask:0xf bound_ctrl:1
	s_nop 1
	v_add_f32_dpp v126, v126, v126 row_half_mirror row_mask:0xf bank_mask:0xf bound_ctrl:1
	s_waitcnt lgkmcnt(8)
	v_pk_fma_f32 v[24:25], v[40:41], v[126:127], v[24:25] op_sel_hi:[1,0,1]
	v_pk_fma_f32 v[26:27], v[42:43], v[126:127], v[26:27] op_sel_hi:[1,0,1]
	v_pk_fma_f32 v[28:29], v[44:45], v[126:127], v[28:29] op_sel_hi:[1,0,1]
	v_pk_fma_f32 v[30:31], v[46:47], v[126:127], v[30:31] op_sel_hi:[1,0,1]
	v_pk_fma_f32 v[102:103], v[102:103], v[16:17], v[24:25]
	v_pk_fma_f32 v[104:105], v[104:105], v[18:19], v[26:27]
	v_pk_fma_f32 v[106:107], v[106:107], v[20:21], v[28:29]
	v_pk_fma_f32 v[108:109], v[108:109], v[22:23], v[30:31]
	ds_read_b128 v[120:123], v114 offset:2576
	ds_read_b128 v[58:61], v114 offset:1792
	ds_read_b128 v[62:65], v114 offset:1808
	s_waitcnt lgkmcnt(9)
	v_pk_mul_f32 v[128:129], v[102:103], v[8:9]
	ds_read_b128 v[50:53], v114 offset:1536
	v_pk_fma_f32 v[128:129], v[104:105], v[10:11], v[128:129]
	ds_read_b128 v[54:57], v114 offset:1552
	v_pk_fma_f32 v[128:129], v[106:107], v[12:13], v[128:129]
	s_waitcnt lgkmcnt(6)
	v_pk_mul_f32 v[66:67], v[66:67], v[124:125] op_sel_hi:[1,0]
	v_pk_fma_f32 v[128:129], v[108:109], v[14:15], v[128:129]
	v_pk_mul_f32 v[68:69], v[68:69], v[124:125] op_sel_hi:[1,0]
	v_add_f32_e32 v128, v128, v129
	v_pk_mul_f32 v[70:71], v[70:71], v[124:125] op_sel_hi:[1,0]
	v_pk_mul_f32 v[72:73], v[72:73], v[124:125] op_sel_hi:[1,0]
	v_add_f32_dpp v128, v128, v128 quad_perm:[1,0,3,2] row_mask:0xf bank_mask:0xf bound_ctrl:1
	s_nop 1
	v_add_f32_dpp v128, v128, v128 quad_perm:[2,3,0,1] row_mask:0xf bank_mask:0xf bound_ctrl:1
	s_nop 1
	v_add_f32_dpp v128, v128, v128 row_half_mirror row_mask:0xf bank_mask:0xf bound_ctrl:1
	s_and_saveexec_b64 s[6:7], s[4:5]
	global_store_dword v[98:99], v128, off
	s_or_b64 exec, exec, s[6:7]
	v_pk_mul_f32 v[126:127], v[102:103], v[74:75]
	ds_read_b128 v[32:35], v114 offset:3840
	v_pk_fma_f32 v[126:127], v[104:105], v[76:77], v[126:127]
	ds_read_b128 v[36:39], v114 offset:3856
	v_pk_fma_f32 v[126:127], v[106:107], v[78:79], v[126:127]
	ds_read_b128 v[24:27], v114 offset:3584
	v_pk_fma_f32 v[126:127], v[108:109], v[80:81], v[126:127]
	ds_read_b128 v[28:31], v114 offset:3600
	v_add_f32_e32 v126, v126, v127
	ds_read_b32 v48, v115 offset:3072
	ds_read_b128 v[40:43], v114 offset:4096
	v_add_f32_dpp v126, v126, v126 quad_perm:[1,0,3,2] row_mask:0xf bank_mask:0xf bound_ctrl:1
	s_nop 1
	v_add_f32_dpp v126, v126, v126 quad_perm:[2,3,0,1] row_mask:0xf bank_mask:0xf bound_ctrl:1
	s_nop 1
	v_add_f32_dpp v126, v126, v126 row_half_mirror row_mask:0xf bank_mask:0xf bound_ctrl:1
	s_waitcnt lgkmcnt(8)
	v_pk_fma_f32 v[66:67], v[116:117], v[126:127], v[66:67] op_sel_hi:[1,0,1]
	v_pk_fma_f32 v[68:69], v[118:119], v[126:127], v[68:69] op_sel_hi:[1,0,1]
	v_pk_fma_f32 v[70:71], v[120:121], v[126:127], v[70:71] op_sel_hi:[1,0,1]
	v_pk_fma_f32 v[72:73], v[122:123], v[126:127], v[72:73] op_sel_hi:[1,0,1]
	v_pk_fma_f32 v[102:103], v[102:103], v[58:59], v[66:67]
	v_pk_fma_f32 v[104:105], v[104:105], v[60:61], v[68:69]
	v_pk_fma_f32 v[106:107], v[106:107], v[62:63], v[70:71]
	v_pk_fma_f32 v[108:109], v[108:109], v[64:65], v[72:73]
	ds_read_b128 v[44:47], v114 offset:4112
	ds_read_b128 v[16:19], v114 offset:3328
	ds_read_b128 v[20:23], v114 offset:3344
	s_waitcnt lgkmcnt(9)
	v_pk_mul_f32 v[128:129], v[102:103], v[50:51]
	ds_read_b128 v[8:11], v114 offset:3072
	v_pk_fma_f32 v[128:129], v[104:105], v[52:53], v[128:129]
	ds_read_b128 v[12:15], v114 offset:3088
	v_pk_fma_f32 v[128:129], v[106:107], v[54:55], v[128:129]
	s_waitcnt lgkmcnt(6)
	v_pk_mul_f32 v[24:25], v[24:25], v[48:49] op_sel_hi:[1,0]
	v_pk_fma_f32 v[128:129], v[108:109], v[56:57], v[128:129]
	v_pk_mul_f32 v[26:27], v[26:27], v[48:49] op_sel_hi:[1,0]
	v_add_f32_e32 v128, v128, v129
	v_pk_mul_f32 v[28:29], v[28:29], v[48:49] op_sel_hi:[1,0]
	v_pk_mul_f32 v[30:31], v[30:31], v[48:49] op_sel_hi:[1,0]
	v_add_f32_dpp v128, v128, v128 quad_perm:[1,0,3,2] row_mask:0xf bank_mask:0xf bound_ctrl:1
	s_nop 1
	v_add_f32_dpp v128, v128, v128 quad_perm:[2,3,0,1] row_mask:0xf bank_mask:0xf bound_ctrl:1
	s_nop 1
	v_add_f32_dpp v128, v128, v128 row_half_mirror row_mask:0xf bank_mask:0xf bound_ctrl:1
	s_and_saveexec_b64 s[6:7], s[4:5]
	global_store_dword v[110:111], v128, off offset:-4
	s_or_b64 exec, exec, s[6:7]
	v_add_u32_e32 v114, 0xc00, v114
	v_add_u32_e32 v115, 0xc00, v115
	v_lshl_add_u64 v[98:99], v[98:99], 0, s[100:101]
	v_lshl_add_u64 v[110:111], v[110:111], 0, s[100:101]
	s_add_i32 s10, s10, 1
	s_cmp_lg_u32 s10, 8
	s_cbranch_scc1 .Lscan8_step
; __device__ __forceinline__ void wkv_scan(unsigned char* ws, int scan, float* lds, int wv_) {
;     ...
;   auto pload = [&](int c) {
;     int si = c * CH + ps;
;     int t = dir ? (SEQ_ - 1 - si) : si;
;     size_t off = ((size_t)(b * SEQ_ + t)) * BW_ + h * 64 + pk;
;     ur = *(const uint2*)(Rr + off); uv = *(const uint2*)(Rv + off); uk = *(const uint2*)(Rk + off);
;     ukk = *(const uint2*)(Rkk + off); ua = *(const uint2*)(Ra + off); ud = *(const uint2*)(Rd + off);
;   };
;   auto pstore = [&](int c) {
;     float r4[4] = {bflo(ur.x), bfhi(ur.x), bflo(ur.y), bfhi(ur.y)};
;     float v4[4] = {bflo(uv.x), bfhi(uv.x), bflo(uv.y), bfhi(uv.y)};
;     float k4[4] = {bflo(uk.x), bfhi(uk.x), bflo(uk.y), bfhi(uk.y)};
;     float q4[4] = {bflo(ukk.x), bfhi(ukk.x), bflo(ukk.y), bfhi(ukk.y)};
;     float a4[4] = {bflo(ua.x), bfhi(ua.x), bflo(ua.y), bfhi(ua.y)};
;     float d4[4] = {bflo(ud.x), bfhi(ud.x), bflo(ud.y), bfhi(ud.y)};
;     float kav[4] = {ka4.x, ka4.y, ka4.z, ka4.w};
;     float* dst = lds + (c & 1) * (CH * STEPF) + ps * STEPF + pk;
;     float4 o;
;     o = make_float4(r4[0], r4[1], r4[2], r4[3]); *(float4*)(dst + 0) = o;
;     o = make_float4(1.f - d4[0], 1.f - d4[1], 1.f - d4[2], 1.f - d4[3]); *(float4*)(dst + 64) = o;
;     o = make_float4(k4[0] * (1.f + (a4[0] - 1.f) * kav[0]), k4[1] * (1.f + (a4[1] - 1.f) * kav[1]),
;                     k4[2] * (1.f + (a4[2] - 1.f) * kav[2]), k4[3] * (1.f + (a4[3] - 1.f) * kav[3]));
;     *(float4*)(dst + 128) = o;
;     o = make_float4(-q4[0], -q4[1], -q4[2], -q4[3]); *(float4*)(dst + 192) = o;
;     o = make_float4(q4[0] * a4[0], q4[1] * a4[1], q4[2] * a4[2], q4[3] * a4[3]); *(float4*)(dst + 256) = o;
;     o = make_float4(v4[0], v4[1], v4[2], v4[3]); *(float4*)(dst + 320) = o;
;   };
;   const int ks = lane & 7, rp = wave * 8 + (lane >> 3);
;   float* yp = Y + ((size_t)(b * SEQ_ + (dir ? SEQ_ - 1 : 0))) * BW_ + h * 64 + 2 * rp;
;   const long ystep = dir ? -(long)BW_ : (long)BW_;
;   float2v S0[4], S1[4];
; #pragma unroll
;   for (int i = 0; i < 4; ++i) { S0[i] = float2v{0.f, 0.f}; S1[i] = float2v{0.f, 0.f}; }
;   __syncthreads();
;   if (wave >= 4) { pload(0); pstore(0); pload(1); }
;   __syncthreads();
;   for (int c = 0; c < NCH; ++c) {
;     if (wave >= 4) {
;       if (c + 1 < NCH) pstore(c + 1);
;       if (c + 2 < NCH) pload(c + 2);
.LBB0_275:
	s_mov_b64 s[2:3], exec
	s_andn2_b64 exec, exec, vcc
	s_cbranch_execz .LBB0_267
	s_waitcnt lgkmcnt(0)
	s_cmpk_eq_i32 s8, 0x7f
	s_cbranch_scc1 .LBB0_278
	s_waitcnt vmcnt(12)
	s_bitcmp1_b32 s8, 0
	s_cselect_b32 s6, 0, 0x6000
	v_lshlrev_b32_e32 v4, 16, v84
	v_and_b32_e32 v5, 0xffff0000, v84
	v_lshlrev_b32_e32 v6, 16, v85
	v_and_b32_e32 v7, 0xffff0000, v85
	v_lshlrev_b32_e32 v24, 16, v92
	v_and_b32_e32 v25, 0xffff0000, v92
	v_lshlrev_b32_e32 v26, 16, v93
	v_and_b32_e32 v27, 0xffff0000, v93
	v_add_u32_e32 v28, s6, v82
	v_lshlrev_b32_e32 v20, 16, v94
	v_and_b32_e32 v21, 0xffff0000, v94
	v_lshlrev_b32_e32 v22, 16, v95
	v_and_b32_e32 v23, 0xffff0000, v95
	ds_write_b128 v28, v[4:7]
	v_pk_add_f32 v[4:5], v[24:25], 1.0 op_sel_hi:[1,0] neg_lo:[1,0] neg_hi:[1,0]
	v_pk_add_f32 v[6:7], v[26:27], 1.0 op_sel_hi:[1,0] neg_lo:[1,0] neg_hi:[1,0]
	ds_write_b128 v28, v[4:7] offset:256
	v_pk_add_f32 v[4:5], v[20:21], -1.0 op_sel_hi:[1,0]
	v_pk_add_f32 v[6:7], v[22:23], -1.0 op_sel_hi:[1,0]
	v_lshlrev_b32_e32 v12, 16, v88
	v_and_b32_e32 v13, 0xffff0000, v88
	v_lshlrev_b32_e32 v14, 16, v89
	v_and_b32_e32 v15, 0xffff0000, v89
	v_pk_fma_f32 v[4:5], v[0:1], v[4:5], 1.0 op_sel_hi:[1,1,0]
	v_pk_fma_f32 v[6:7], v[2:3], v[6:7], 1.0 op_sel_hi:[1,1,0]
	v_lshlrev_b32_e32 v16, 16, v90
	v_and_b32_e32 v17, 0xffff0000, v90
	v_lshlrev_b32_e32 v18, 16, v91
	v_and_b32_e32 v19, 0xffff0000, v91
	v_pk_mul_f32 v[4:5], v[4:5], v[12:13]
	v_pk_mul_f32 v[6:7], v[6:7], v[14:15]
	ds_write_b128 v28, v[4:7] offset:512
	v_xor_b32_e32 v5, 0x80000000, v17
	v_xor_b32_e32 v4, 0x80000000, v16
	v_xor_b32_e32 v7, 0x80000000, v19
	v_xor_b32_e32 v6, 0x80000000, v18
	ds_write_b128 v28, v[4:7] offset:768
	v_pk_mul_f32 v[4:5], v[16:17], v[20:21]
	v_pk_mul_f32 v[6:7], v[18:19], v[22:23]
	v_lshlrev_b32_e32 v8, 16, v86
	v_and_b32_e32 v9, 0xffff0000, v86
	v_lshlrev_b32_e32 v10, 16, v87
	v_and_b32_e32 v11, 0xffff0000, v87
	ds_write_b128 v28, v[4:7] offset:1024
	ds_write_b128 v28, v[8:11] offset:1280
.LBB0_278:
	s_cmpk_gt_u32 s8, 0x7d
	s_cbranch_scc1 .LBB0_267
	v_lshl_add_u32 v4, s8, 4, v83
	v_readlane_b32 s6, v251, 28
	v_sub_u32_e32 v5, 0x7ff, v4
	v_readlane_b32 s7, v251, 29
	s_nop 1
	v_cndmask_b32_e64 v4, v5, v4, s[6:7]
	v_readlane_b32 s6, v251, 27
	s_nop 1
	v_add_u32_e32 v4, s6, v4
	v_mad_i64_i32 v[4:5], s[6:7], v4, s33, v[100:101]
	v_lshlrev_b64 v[4:5], 1, v[4:5]
	v_readlane_b32 s6, v251, 21
	v_lshl_add_u64 v[6:7], s[28:29], 0, v[4:5]
	v_readlane_b32 s7, v251, 22
	v_lshl_add_u64 v[8:9], s[30:31], 0, v[4:5]
	v_lshl_add_u64 v[10:11], s[66:67], 0, v[4:5]
	v_lshl_add_u64 v[12:13], s[82:83], 0, v[4:5]
	global_load_dwordx2 v[84:85], v[6:7], off
	global_load_dwordx2 v[86:87], v[8:9], off
	global_load_dwordx2 v[88:89], v[10:11], off
	global_load_dwordx2 v[90:91], v[12:13], off
	v_lshl_add_u64 v[6:7], s[6:7], 0, v[4:5]
	v_readlane_b32 s6, v251, 25
	v_readlane_b32 s7, v251, 26
	s_nop 1
	v_lshl_add_u64 v[4:5], s[6:7], 0, v[4:5]
	global_load_dwordx2 v[94:95], v[6:7], off
	global_load_dwordx2 v[92:93], v[4:5], off
	s_branch .LBB0_267
